# grid barrier: non-leader workgroups invalidate their L1 before parking in the poll loop instead of after release
# speedup vs baseline: 1.0118x; 1.0118x over previous
; DI unsigned xb_ld(unsigned* p)              { return __hip_atomic_load(p, __ATOMIC_RELAXED, __HIP_MEMORY_SCOPE_AGENT); }
; DI unsigned xb_add(unsigned* p, unsigned v) { return __hip_atomic_fetch_add(p, v, __ATOMIC_RELAXED, __HIP_MEMORY_SCOPE_AGENT); }
; #define XB_SPIN(cond, bar) do { unsigned _sp = 0; while (cond) { __builtin_amdgcn_s_sleep(1); \
;     if ((++_sp & 255u) == 0u) { if (xb_ld(&(bar)[XB_TMO])) break; if (_sp > XB_SPIN_CAP) { atomicAdd(&(bar)[XB_TMO], 1u); break; } } } } while (0)
; DI void xcd_barrier(const XcdBarrier& b) {
;     ...
;         const unsigned old = xb_add(&bar[XB_XSUB(b.x)], 1u);
;         const unsigned gen = old / nloc;
;         if (old + 1u == (gen + 1u) * nloc) {
;             __builtin_amdgcn_fence(__ATOMIC_RELEASE, "agent");
;             asm volatile("s_waitcnt vmcnt(0)" ::: "memory");
;             const unsigned og = xb_add(&bar[XB_TOP], 1u);
;             const unsigned tg = og / nx;
;             if (og + 1u == (tg + 1u) * nx) xb_add(&bar[XB_TOPGEN], 1u);
;             else XB_SPIN(xb_ld(&bar[XB_TOPGEN]) == tg, bar);
;             __builtin_amdgcn_fence(__ATOMIC_ACQUIRE, "agent");
;             xb_add(&bar[XB_XGEN(b.x)], 1u);
;             asm volatile("s_waitcnt vmcnt(0)" ::: "memory");
;         } else {
;             XB_SPIN(xb_ld(&bar[XB_XGEN(b.x)]) == gen, bar);
.LBB0_104:
	s_or_b64 exec, exec, s[10:11]
	v_cvt_f32_u32_e32 v4, v2
	s_waitcnt vmcnt(0)
	v_readfirstlane_b32 s8, v3
	v_sub_u32_e32 v3, 0, v2
	v_rcp_iflag_f32_e32 v4, v4
	v_add_u32_e32 v5, s8, v1
	v_mul_f32_e32 v4, 0x4f7ffffe, v4
	v_cvt_u32_f32_e32 v4, v4
	v_mul_lo_u32 v1, v3, v4
	v_mul_hi_u32 v1, v4, v1
	v_add_u32_e32 v1, v4, v1
	v_mul_hi_u32 v1, v5, v1
	v_mul_lo_u32 v3, v1, v2
	v_sub_u32_e32 v3, v5, v3
	v_add_u32_e32 v4, 1, v1
	v_cmp_ge_u32_e32 vcc, v3, v2
	s_nop 1
	v_cndmask_b32_e32 v1, v1, v4, vcc
	v_sub_u32_e32 v4, v3, v2
	v_cndmask_b32_e32 v3, v3, v4, vcc
	v_add_u32_e32 v4, 1, v1
	v_cmp_ge_u32_e32 vcc, v3, v2
	v_add_u32_e32 v3, 1, v5
	s_nop 0
	v_cndmask_b32_e32 v1, v1, v4, vcc
	v_mul_lo_u32 v4, v2, v1
	v_add_u32_e32 v2, v4, v2
	v_cmp_ne_u32_e32 vcc, v3, v2
	s_and_saveexec_b64 s[8:9], vcc
	s_xor_b64 s[8:9], exec, s[8:9]
	s_cbranch_execz .LBB0_118
	s_waitcnt lgkmcnt(0)
	buffer_inv sc1
	v_mov_b32_e32 v0, 0x2000
	global_load_dword v0, v0, s[6:7] offset:1024 sc1
	s_add_u32 s14, s6, 0x2400
	s_addc_u32 s15, s7, 0
	s_waitcnt vmcnt(0)
	v_cmp_eq_u32_e32 vcc, v0, v1
	s_and_saveexec_b64 s[10:11], vcc
	s_cbranch_execz .LBB0_117
	s_add_u32 s12, s44, 0xf690200
	s_addc_u32 s13, s45, 0
	s_mov_b32 s26, 1
	s_mov_b64 s[16:17], 0
	v_mov_b32_e32 v0, 0
	s_branch .LBB0_108

; DI unsigned xb_ld(unsigned* p)              { return __hip_atomic_load(p, __ATOMIC_RELAXED, __HIP_MEMORY_SCOPE_AGENT); }
; #define XB_SPIN(cond, bar) do { unsigned _sp = 0; while (cond) { __builtin_amdgcn_s_sleep(1); \
;     if ((++_sp & 255u) == 0u) { if (xb_ld(&(bar)[XB_TMO])) break; if (_sp > XB_SPIN_CAP) { atomicAdd(&(bar)[XB_TMO], 1u); break; } } } } while (0)
; DI void xcd_barrier(const XcdBarrier& b) {
;     ...
;         } else {
;             XB_SPIN(xb_ld(&bar[XB_XGEN(b.x)]) == gen, bar);
;             __builtin_amdgcn_fence(__ATOMIC_ACQUIRE, "agent");
;             asm volatile("s_waitcnt vmcnt(0)" ::: "memory");
.LBB0_117:
	s_or_b64 exec, exec, s[10:11]
	s_waitcnt vmcnt(0)
	s_waitcnt vmcnt(0)

; DI unsigned xb_ld(unsigned* p)              { return __hip_atomic_load(p, __ATOMIC_RELAXED, __HIP_MEMORY_SCOPE_AGENT); }
; DI unsigned xb_add(unsigned* p, unsigned v) { return __hip_atomic_fetch_add(p, v, __ATOMIC_RELAXED, __HIP_MEMORY_SCOPE_AGENT); }
; #define XB_SPIN(cond, bar) do { unsigned _sp = 0; while (cond) { __builtin_amdgcn_s_sleep(1); \
;     if ((++_sp & 255u) == 0u) { if (xb_ld(&(bar)[XB_TMO])) break; if (_sp > XB_SPIN_CAP) { atomicAdd(&(bar)[XB_TMO], 1u); break; } } } } while (0)
; DI void xcd_barrier(const XcdBarrier& b) {
;     ...
;         const unsigned old = xb_add(&bar[XB_XSUB(b.x)], 1u);
;         const unsigned gen = old / nloc;
;         if (old + 1u == (gen + 1u) * nloc) {
;             __builtin_amdgcn_fence(__ATOMIC_RELEASE, "agent");
;             asm volatile("s_waitcnt vmcnt(0)" ::: "memory");
;             const unsigned og = xb_add(&bar[XB_TOP], 1u);
;             const unsigned tg = og / nx;
;             if (og + 1u == (tg + 1u) * nx) xb_add(&bar[XB_TOPGEN], 1u);
;             else XB_SPIN(xb_ld(&bar[XB_TOPGEN]) == tg, bar);
;             __builtin_amdgcn_fence(__ATOMIC_ACQUIRE, "agent");
;             xb_add(&bar[XB_XGEN(b.x)], 1u);
;             asm volatile("s_waitcnt vmcnt(0)" ::: "memory");
;         } else {
;             XB_SPIN(xb_ld(&bar[XB_XGEN(b.x)]) == gen, bar);
.LBB0_1325:
	s_or_b64 exec, exec, s[12:13]
	v_cvt_f32_u32_e32 v4, v2
	s_waitcnt vmcnt(0)
	v_readfirstlane_b32 s10, v3
	v_sub_u32_e32 v3, 0, v2
	v_rcp_iflag_f32_e32 v4, v4
	v_add_u32_e32 v5, s10, v1
	v_mul_f32_e32 v4, 0x4f7ffffe, v4
	v_cvt_u32_f32_e32 v4, v4
	v_mul_lo_u32 v1, v3, v4
	v_mul_hi_u32 v1, v4, v1
	v_add_u32_e32 v1, v4, v1
	v_mul_hi_u32 v1, v5, v1
	v_mul_lo_u32 v3, v1, v2
	v_sub_u32_e32 v3, v5, v3
	v_add_u32_e32 v4, 1, v1
	v_cmp_ge_u32_e32 vcc, v3, v2
	s_nop 1
	v_cndmask_b32_e32 v1, v1, v4, vcc
	v_sub_u32_e32 v4, v3, v2
	v_cndmask_b32_e32 v3, v3, v4, vcc
	v_add_u32_e32 v4, 1, v1
	v_cmp_ge_u32_e32 vcc, v3, v2
	v_add_u32_e32 v3, 1, v5
	s_nop 0
	v_cndmask_b32_e32 v1, v1, v4, vcc
	v_mul_lo_u32 v4, v2, v1
	v_add_u32_e32 v2, v4, v2
	v_cmp_ne_u32_e32 vcc, v3, v2
	s_and_saveexec_b64 s[10:11], vcc
	s_xor_b64 s[10:11], exec, s[10:11]
	s_cbranch_execz .LBB0_1339
	s_waitcnt lgkmcnt(0)
	buffer_inv sc1
	v_mov_b32_e32 v0, 0x2000
	global_load_dword v0, v0, s[8:9] offset:1024 sc1
	s_add_u32 s16, s8, 0x2400
	s_addc_u32 s17, s9, 0
	s_waitcnt vmcnt(0)
	v_cmp_eq_u32_e32 vcc, v0, v1
	s_and_saveexec_b64 s[12:13], vcc
	s_cbranch_execz .LBB0_1338
	s_add_u32 s14, s44, 0xf690200
	s_addc_u32 s15, s45, 0
	s_mov_b32 s28, 1
	s_mov_b64 s[18:19], 0
	v_mov_b32_e32 v0, 0
	s_branch .LBB0_1329

; DI unsigned xb_ld(unsigned* p)              { return __hip_atomic_load(p, __ATOMIC_RELAXED, __HIP_MEMORY_SCOPE_AGENT); }
; #define XB_SPIN(cond, bar) do { unsigned _sp = 0; while (cond) { __builtin_amdgcn_s_sleep(1); \
;     if ((++_sp & 255u) == 0u) { if (xb_ld(&(bar)[XB_TMO])) break; if (_sp > XB_SPIN_CAP) { atomicAdd(&(bar)[XB_TMO], 1u); break; } } } } while (0)
; DI void xcd_barrier(const XcdBarrier& b) {
;     ...
;         } else {
;             XB_SPIN(xb_ld(&bar[XB_XGEN(b.x)]) == gen, bar);
;             __builtin_amdgcn_fence(__ATOMIC_ACQUIRE, "agent");
;             asm volatile("s_waitcnt vmcnt(0)" ::: "memory");
.LBB0_1338:
	s_or_b64 exec, exec, s[12:13]
	s_waitcnt vmcnt(0)
	s_waitcnt vmcnt(0)
